# diff-attn PV MFMAs interleaved into exp stream with V frags staged in AGPRs (loads spread); max3 nops removed
# speedup vs baseline: 1.0590x; 1.0057x over previous
; DI float max3_(float a, float b, float c) { float r; asm("v_max3_f32 %0, %1, %2, %3" : "=v"(r) : "v"(a), "v"(b), "v"(c)); return r; }
; template <int DQK, bool BIAS>
; __device__ __forceinline__ void attn_pass(const hf* __restrict__ Q, int ldq, const hf* __restrict__ Kp, int ldk, const hf* __restrict__ VT,
;                                           int s0, int L, int q0, float scale_l2, const float* sBias, f4 (&oacc)[8][4], char* smem) {
;     ...
;       float mx = -1e30f;
; #pragma unroll
;       for (int mk = 0; mk < 4; ++mk) { mx = max3_(mx, sacc[mk][nq][0], sacc[mk][nq][1]); mx = max3_(mx, sacc[mk][nq][2], sacc[mk][nq][3]); }
;       mx = max3_(mx, shx(mx, 16), mx); mx = max3_(mx, shx(mx, 32), mx);
;       if (!BIAS) mx *= scale_l2;
;       const bool upd = mx > mrun[nq] + 8.f;
;       const float mnew = upd ? mx : mrun[nq];
;       if (__builtin_amdgcn_ballot_w64(upd) != 0) {
;         const float alpha = __builtin_amdgcn_exp2f(mrun[nq] - mnew);
;         lrun[nq] *= alpha;
; #pragma unroll
;         for (int md = 0; md < 8; ++md) { oacc[md][nq][0] *= alpha; oacc[md][nq][1] *= alpha; oacc[md][nq][2] *= alpha; oacc[md][nq][3] *= alpha; }
;       }
.LBB0_1956:
	v_max3_f32 v176, v199, v32, v33
	v_max3_f32 v176, v176, v34, v35
	v_max3_f32 v176, v176, v44, v45
	v_max3_f32 v176, v176, v46, v47
	v_max3_f32 v176, v176, v40, v41
	v_max3_f32 v176, v176, v42, v43
	v_max3_f32 v176, v176, v36, v37
	v_max3_f32 v176, v176, v38, v39
	v_mov_b32_e32 v177, v176
	s_nop 1
	v_permlane16_swap_b32_e32 v177, v176
	v_max_f32_e32 v176, v176, v177
	v_mov_b32_e32 v177, v176
	s_nop 1
	v_permlane32_swap_b32_e32 v177, v176
	v_max_f32_e32 v176, v176, v177
	v_add_f32_e32 v177, 0x41000000, v198
	v_cmp_gt_f32_e32 vcc, v176, v177
	s_nop 1
	v_cndmask_b32_e32 v176, v198, v176, vcc
	s_cbranch_vccz .LBB0_1958
	v_accvgpr_read_b32 v55, a95
	v_accvgpr_read_b32 v51, a107
	v_accvgpr_read_b32 v56, a76
	v_accvgpr_read_b32 v60, a64
	v_accvgpr_read_b32 v64, a44
	v_accvgpr_read_b32 v72, a24
	v_accvgpr_read_b32 v68, a8
	v_accvgpr_read_b32 v76, a0
	v_accvgpr_read_b32 v50, a106
	v_accvgpr_read_b32 v49, a105
	v_accvgpr_read_b32 v48, a104
	v_accvgpr_read_b32 v54, a94
	v_accvgpr_read_b32 v53, a93
	v_accvgpr_read_b32 v52, a92
	v_accvgpr_read_b32 v57, a77
	v_accvgpr_read_b32 v58, a78
	v_accvgpr_read_b32 v59, a79
	v_accvgpr_read_b32 v61, a65
	v_accvgpr_read_b32 v62, a66
	v_accvgpr_read_b32 v63, a67
	v_accvgpr_read_b32 v65, a45
	v_accvgpr_read_b32 v66, a46
	v_accvgpr_read_b32 v67, a47
	v_accvgpr_read_b32 v73, a25
	v_accvgpr_read_b32 v74, a26
	v_accvgpr_read_b32 v75, a27
	v_accvgpr_read_b32 v69, a9
	v_accvgpr_read_b32 v70, a10
	v_accvgpr_read_b32 v71, a11
	v_accvgpr_read_b32 v77, a1
	v_accvgpr_read_b32 v78, a2
	v_accvgpr_read_b32 v79, a3
	v_sub_f32_e32 v177, v198, v176
	v_exp_f32_e32 v178, v177
	s_nop 0
	v_pk_mul_f32 v[76:77], v[76:77], v[178:179] op_sel_hi:[1,0]
	v_pk_mul_f32 v[68:69], v[68:69], v[178:179] op_sel_hi:[1,0]
	v_pk_mul_f32 v[72:73], v[72:73], v[178:179] op_sel_hi:[1,0]
	v_pk_mul_f32 v[64:65], v[64:65], v[178:179] op_sel_hi:[1,0]
	v_pk_mul_f32 v[60:61], v[60:61], v[178:179] op_sel_hi:[1,0]
	v_pk_mul_f32 v[56:57], v[56:57], v[178:179] op_sel_hi:[1,0]
	v_pk_mul_f32 v[54:55], v[54:55], v[178:179] op_sel_hi:[1,0]
	v_pk_mul_f32 v[50:51], v[50:51], v[178:179] op_sel_hi:[1,0]
	v_pk_mul_f32 v[78:79], v[78:79], v[178:179] op_sel_hi:[1,0]
	v_pk_mul_f32 v[70:71], v[70:71], v[178:179] op_sel_hi:[1,0]
	v_pk_mul_f32 v[74:75], v[74:75], v[178:179] op_sel_hi:[1,0]
	v_pk_mul_f32 v[66:67], v[66:67], v[178:179] op_sel_hi:[1,0]
	v_pk_mul_f32 v[62:63], v[62:63], v[178:179] op_sel_hi:[1,0]
	v_pk_mul_f32 v[58:59], v[58:59], v[178:179] op_sel_hi:[1,0]
	v_pk_mul_f32 v[52:53], v[52:53], v[178:179] op_sel_hi:[1,0]
	v_pk_mul_f32 v[48:49], v[48:49], v[178:179] op_sel_hi:[1,0]
	v_accvgpr_write_b32 a95, v55
	v_accvgpr_write_b32 a107, v51
	v_accvgpr_write_b32 a76, v56
	v_accvgpr_write_b32 a64, v60
	v_accvgpr_write_b32 a44, v64
	v_accvgpr_write_b32 a24, v72
	v_accvgpr_write_b32 a8, v68
	v_accvgpr_write_b32 a0, v76
	v_mul_f32_e32 v245, v245, v178
	v_accvgpr_write_b32 a106, v50
	v_accvgpr_write_b32 a105, v49
	v_accvgpr_write_b32 a104, v48
	v_accvgpr_write_b32 a94, v54
	v_accvgpr_write_b32 a93, v53
	v_accvgpr_write_b32 a92, v52
	v_accvgpr_write_b32 a77, v57
	v_accvgpr_write_b32 a78, v58
	v_accvgpr_write_b32 a79, v59
	v_accvgpr_write_b32 a65, v61
	v_accvgpr_write_b32 a66, v62
	v_accvgpr_write_b32 a67, v63
	v_accvgpr_write_b32 a45, v65
	v_accvgpr_write_b32 a46, v66
	v_accvgpr_write_b32 a47, v67
	v_accvgpr_write_b32 a25, v73
	v_accvgpr_write_b32 a26, v74
	v_accvgpr_write_b32 a27, v75
	v_accvgpr_write_b32 a9, v69
	v_accvgpr_write_b32 a10, v70
	v_accvgpr_write_b32 a11, v71
	v_accvgpr_write_b32 a1, v77
	v_accvgpr_write_b32 a2, v78
	v_accvgpr_write_b32 a3, v79

; DI float max3_(float a, float b, float c) { float r; asm("v_max3_f32 %0, %1, %2, %3" : "=v"(r) : "v"(a), "v"(b), "v"(c)); return r; }
; template <int DQK, bool BIAS>
; __device__ __forceinline__ void attn_pass(const hf* __restrict__ Q, int ldq, const hf* __restrict__ Kp, int ldk, const hf* __restrict__ VT,
;                                           int s0, int L, int q0, float scale_l2, const float* sBias, f4 (&oacc)[8][4], char* smem) {
;     ...
;       float mx = -1e30f;
; #pragma unroll
;       for (int mk = 0; mk < 4; ++mk) { mx = max3_(mx, sacc[mk][nq][0], sacc[mk][nq][1]); mx = max3_(mx, sacc[mk][nq][2], sacc[mk][nq][3]); }
;       mx = max3_(mx, shx(mx, 16), mx); mx = max3_(mx, shx(mx, 32), mx);
;       if (!BIAS) mx *= scale_l2;
;       const bool upd = mx > mrun[nq] + 8.f;
;       const float mnew = upd ? mx : mrun[nq];
;       if (__builtin_amdgcn_ballot_w64(upd) != 0) {
;         const float alpha = __builtin_amdgcn_exp2f(mrun[nq] - mnew);
;         lrun[nq] *= alpha;
; #pragma unroll
;         for (int md = 0; md < 8; ++md) { oacc[md][nq][0] *= alpha; oacc[md][nq][1] *= alpha; oacc[md][nq][2] *= alpha; oacc[md][nq][3] *= alpha; }
;       }
.LBB0_1962:
	v_max3_f32 v160, v199, v80, v81
	v_max3_f32 v160, v160, v82, v83
	v_max3_f32 v160, v160, v92, v93
	v_max3_f32 v160, v160, v94, v95
	v_max3_f32 v160, v160, v84, v85
	v_max3_f32 v160, v160, v86, v87
	v_max3_f32 v160, v160, v88, v89
	v_max3_f32 v160, v160, v90, v91
	v_mov_b32_e32 v161, v160
	s_nop 1
	v_permlane16_swap_b32_e32 v161, v160
	v_max_f32_e32 v160, v160, v161
	v_mov_b32_e32 v161, v160
	s_nop 1
	v_permlane32_swap_b32_e32 v161, v160
	v_max_f32_e32 v160, v160, v161
	v_add_f32_e32 v161, 0x41000000, v253
	v_cmp_gt_f32_e32 vcc, v160, v161
	s_nop 1
	v_cndmask_b32_e32 v160, v253, v160, vcc
	s_cbranch_vccz .LBB0_1964
	v_accvgpr_read_b32 v52, a100
	v_accvgpr_read_b32 v48, a116
	v_accvgpr_read_b32 v56, a84
	v_accvgpr_read_b32 v60, a68
	v_accvgpr_read_b32 v64, a52
	v_accvgpr_read_b32 v72, a36
	v_accvgpr_read_b32 v68, a16
	v_accvgpr_read_b32 v76, a4
	v_accvgpr_read_b32 v49, a117
	v_accvgpr_read_b32 v50, a118
	v_accvgpr_read_b32 v51, a119
	v_accvgpr_read_b32 v53, a101
	v_accvgpr_read_b32 v54, a102
	v_accvgpr_read_b32 v55, a103
	v_accvgpr_read_b32 v57, a85
	v_accvgpr_read_b32 v58, a86
	v_accvgpr_read_b32 v59, a87
	v_accvgpr_read_b32 v61, a69
	v_accvgpr_read_b32 v62, a70
	v_accvgpr_read_b32 v63, a71
	v_accvgpr_read_b32 v65, a53
	v_accvgpr_read_b32 v66, a54
	v_accvgpr_read_b32 v67, a55
	v_accvgpr_read_b32 v73, a37
	v_accvgpr_read_b32 v74, a38
	v_accvgpr_read_b32 v75, a39
	v_accvgpr_read_b32 v69, a17
	v_accvgpr_read_b32 v70, a18
	v_accvgpr_read_b32 v71, a19
	v_accvgpr_read_b32 v77, a5
	v_accvgpr_read_b32 v78, a6
	v_accvgpr_read_b32 v79, a7
	v_sub_f32_e32 v161, v253, v160
	v_exp_f32_e32 v162, v161
	s_nop 0
	v_pk_mul_f32 v[76:77], v[76:77], v[162:163] op_sel_hi:[1,0]
	v_pk_mul_f32 v[68:69], v[68:69], v[162:163] op_sel_hi:[1,0]
	v_pk_mul_f32 v[72:73], v[72:73], v[162:163] op_sel_hi:[1,0]
	v_pk_mul_f32 v[64:65], v[64:65], v[162:163] op_sel_hi:[1,0]
	v_pk_mul_f32 v[60:61], v[60:61], v[162:163] op_sel_hi:[1,0]
	v_pk_mul_f32 v[56:57], v[56:57], v[162:163] op_sel_hi:[1,0]
	v_pk_mul_f32 v[52:53], v[52:53], v[162:163] op_sel_hi:[1,0]
	v_pk_mul_f32 v[48:49], v[48:49], v[162:163] op_sel_hi:[1,0]
	v_pk_mul_f32 v[78:79], v[78:79], v[162:163] op_sel_hi:[1,0]
	v_pk_mul_f32 v[70:71], v[70:71], v[162:163] op_sel_hi:[1,0]
	v_pk_mul_f32 v[74:75], v[74:75], v[162:163] op_sel_hi:[1,0]
	v_pk_mul_f32 v[66:67], v[66:67], v[162:163] op_sel_hi:[1,0]
	v_pk_mul_f32 v[62:63], v[62:63], v[162:163] op_sel_hi:[1,0]
	v_pk_mul_f32 v[58:59], v[58:59], v[162:163] op_sel_hi:[1,0]
	v_pk_mul_f32 v[54:55], v[54:55], v[162:163] op_sel_hi:[1,0]
	v_pk_mul_f32 v[50:51], v[50:51], v[162:163] op_sel_hi:[1,0]
	v_accvgpr_write_b32 a100, v52
	v_accvgpr_write_b32 a116, v48
	v_accvgpr_write_b32 a84, v56
	v_accvgpr_write_b32 a68, v60
	v_accvgpr_write_b32 a52, v64
	v_accvgpr_write_b32 a36, v72
	v_accvgpr_write_b32 a16, v68
	v_accvgpr_write_b32 a4, v76
	v_mul_f32_e32 v243, v243, v162
	v_accvgpr_write_b32 a117, v49
	v_accvgpr_write_b32 a118, v50
	v_accvgpr_write_b32 a119, v51
	v_accvgpr_write_b32 a101, v53
	v_accvgpr_write_b32 a102, v54
	v_accvgpr_write_b32 a103, v55
	v_accvgpr_write_b32 a85, v57
	v_accvgpr_write_b32 a86, v58
	v_accvgpr_write_b32 a87, v59
	v_accvgpr_write_b32 a69, v61
	v_accvgpr_write_b32 a70, v62
	v_accvgpr_write_b32 a71, v63
	v_accvgpr_write_b32 a53, v65
	v_accvgpr_write_b32 a54, v66
	v_accvgpr_write_b32 a55, v67
	v_accvgpr_write_b32 a37, v73
	v_accvgpr_write_b32 a38, v74
	v_accvgpr_write_b32 a39, v75
	v_accvgpr_write_b32 a17, v69
	v_accvgpr_write_b32 a18, v70
	v_accvgpr_write_b32 a19, v71
	v_accvgpr_write_b32 a5, v77
	v_accvgpr_write_b32 a6, v78
	v_accvgpr_write_b32 a7, v79

; DI float max3_(float a, float b, float c) { float r; asm("v_max3_f32 %0, %1, %2, %3" : "=v"(r) : "v"(a), "v"(b), "v"(c)); return r; }
; template <int DQK, bool BIAS>
; __device__ __forceinline__ void attn_pass(const hf* __restrict__ Q, int ldq, const hf* __restrict__ Kp, int ldk, const hf* __restrict__ VT,
;                                           int s0, int L, int q0, float scale_l2, const float* sBias, f4 (&oacc)[8][4], char* smem) {
;     ...
;       float mx = -1e30f;
; #pragma unroll
;       for (int mk = 0; mk < 4; ++mk) { mx = max3_(mx, sacc[mk][nq][0], sacc[mk][nq][1]); mx = max3_(mx, sacc[mk][nq][2], sacc[mk][nq][3]); }
;       mx = max3_(mx, shx(mx, 16), mx); mx = max3_(mx, shx(mx, 32), mx);
;       if (!BIAS) mx *= scale_l2;
;       const bool upd = mx > mrun[nq] + 8.f;
;       const float mnew = upd ? mx : mrun[nq];
;       if (__builtin_amdgcn_ballot_w64(upd) != 0) {
;         const float alpha = __builtin_amdgcn_exp2f(mrun[nq] - mnew);
;         lrun[nq] *= alpha;
; #pragma unroll
;         for (int md = 0; md < 8; ++md) { oacc[md][nq][0] *= alpha; oacc[md][nq][1] *= alpha; oacc[md][nq][2] *= alpha; oacc[md][nq][3] *= alpha; }
;       }
.LBB0_1968:
	v_max3_f32 v144, v199, v128, v129
	v_max3_f32 v144, v144, v130, v131
	v_max3_f32 v144, v144, v140, v141
	v_max3_f32 v144, v144, v142, v143
	v_max3_f32 v144, v144, v136, v137
	v_max3_f32 v144, v144, v138, v139
	v_max3_f32 v144, v144, v132, v133
	v_max3_f32 v144, v144, v134, v135
	v_mov_b32_e32 v145, v144
	s_nop 1
	v_permlane16_swap_b32_e32 v145, v144
	v_max_f32_e32 v144, v144, v145
	v_mov_b32_e32 v145, v144
	s_nop 1
	v_permlane32_swap_b32_e32 v145, v144
	v_max_f32_e32 v144, v144, v145
	v_add_f32_e32 v145, 0x41000000, v247
	v_cmp_gt_f32_e32 vcc, v144, v145
	s_nop 1
	v_cndmask_b32_e32 v144, v247, v144, vcc
	s_cbranch_vccz .LBB0_1970
	v_accvgpr_read_b32 v55, a111
	v_accvgpr_read_b32 v51, a123
	v_accvgpr_read_b32 v56, a88
	v_accvgpr_read_b32 v60, a72
	v_accvgpr_read_b32 v64, a56
	v_accvgpr_read_b32 v72, a40
	v_accvgpr_read_b32 v68, a28
	v_accvgpr_read_b32 v76, a12
	v_accvgpr_read_b32 v50, a122
	v_accvgpr_read_b32 v49, a121
	v_accvgpr_read_b32 v48, a120
	v_accvgpr_read_b32 v54, a110
	v_accvgpr_read_b32 v53, a109
	v_accvgpr_read_b32 v52, a108
	v_accvgpr_read_b32 v57, a89
	v_accvgpr_read_b32 v58, a90
	v_accvgpr_read_b32 v59, a91
	v_accvgpr_read_b32 v61, a73
	v_accvgpr_read_b32 v62, a74
	v_accvgpr_read_b32 v63, a75
	v_accvgpr_read_b32 v65, a57
	v_accvgpr_read_b32 v66, a58
	v_accvgpr_read_b32 v67, a59
	v_accvgpr_read_b32 v73, a41
	v_accvgpr_read_b32 v74, a42
	v_accvgpr_read_b32 v75, a43
	v_accvgpr_read_b32 v69, a29
	v_accvgpr_read_b32 v70, a30
	v_accvgpr_read_b32 v71, a31
	v_accvgpr_read_b32 v77, a13
	v_accvgpr_read_b32 v78, a14
	v_accvgpr_read_b32 v79, a15
	v_sub_f32_e32 v145, v247, v144
	v_exp_f32_e32 v146, v145
	s_nop 0
	v_pk_mul_f32 v[76:77], v[76:77], v[146:147] op_sel_hi:[1,0]
	v_pk_mul_f32 v[68:69], v[68:69], v[146:147] op_sel_hi:[1,0]
	v_pk_mul_f32 v[72:73], v[72:73], v[146:147] op_sel_hi:[1,0]
	v_pk_mul_f32 v[64:65], v[64:65], v[146:147] op_sel_hi:[1,0]
	v_pk_mul_f32 v[60:61], v[60:61], v[146:147] op_sel_hi:[1,0]
	v_pk_mul_f32 v[56:57], v[56:57], v[146:147] op_sel_hi:[1,0]
	v_pk_mul_f32 v[54:55], v[54:55], v[146:147] op_sel_hi:[1,0]
	v_pk_mul_f32 v[50:51], v[50:51], v[146:147] op_sel_hi:[1,0]
	v_pk_mul_f32 v[78:79], v[78:79], v[146:147] op_sel_hi:[1,0]
	v_pk_mul_f32 v[70:71], v[70:71], v[146:147] op_sel_hi:[1,0]
	v_pk_mul_f32 v[74:75], v[74:75], v[146:147] op_sel_hi:[1,0]
	v_pk_mul_f32 v[66:67], v[66:67], v[146:147] op_sel_hi:[1,0]
	v_pk_mul_f32 v[62:63], v[62:63], v[146:147] op_sel_hi:[1,0]
	v_pk_mul_f32 v[58:59], v[58:59], v[146:147] op_sel_hi:[1,0]
	v_pk_mul_f32 v[52:53], v[52:53], v[146:147] op_sel_hi:[1,0]
	v_pk_mul_f32 v[48:49], v[48:49], v[146:147] op_sel_hi:[1,0]
	v_accvgpr_write_b32 a111, v55
	v_accvgpr_write_b32 a123, v51
	v_accvgpr_write_b32 a88, v56
	v_accvgpr_write_b32 a72, v60
	v_accvgpr_write_b32 a56, v64
	v_accvgpr_write_b32 a40, v72
	v_accvgpr_write_b32 a28, v68
	v_accvgpr_write_b32 a12, v76
	v_mul_f32_e32 v242, v242, v146
	v_accvgpr_write_b32 a122, v50
	v_accvgpr_write_b32 a121, v49
	v_accvgpr_write_b32 a120, v48
	v_accvgpr_write_b32 a110, v54
	v_accvgpr_write_b32 a109, v53
	v_accvgpr_write_b32 a108, v52
	v_accvgpr_write_b32 a89, v57
	v_accvgpr_write_b32 a90, v58
	v_accvgpr_write_b32 a91, v59
	v_accvgpr_write_b32 a73, v61
	v_accvgpr_write_b32 a74, v62
	v_accvgpr_write_b32 a75, v63
	v_accvgpr_write_b32 a57, v65
	v_accvgpr_write_b32 a58, v66
	v_accvgpr_write_b32 a59, v67
	v_accvgpr_write_b32 a41, v73
	v_accvgpr_write_b32 a42, v74
	v_accvgpr_write_b32 a43, v75
	v_accvgpr_write_b32 a29, v69
	v_accvgpr_write_b32 a30, v70
	v_accvgpr_write_b32 a31, v71
	v_accvgpr_write_b32 a13, v77
	v_accvgpr_write_b32 a14, v78
	v_accvgpr_write_b32 a15, v79

; DI float max3_(float a, float b, float c) { float r; asm("v_max3_f32 %0, %1, %2, %3" : "=v"(r) : "v"(a), "v"(b), "v"(c)); return r; }
; template <int DQK, bool BIAS>
; __device__ __forceinline__ void attn_pass(const hf* __restrict__ Q, int ldq, const hf* __restrict__ Kp, int ldk, const hf* __restrict__ VT,
;                                           int s0, int L, int q0, float scale_l2, const float* sBias, f4 (&oacc)[8][4], char* smem) {
;     ...
;       float mx = -1e30f;
; #pragma unroll
;       for (int mk = 0; mk < 4; ++mk) { mx = max3_(mx, sacc[mk][nq][0], sacc[mk][nq][1]); mx = max3_(mx, sacc[mk][nq][2], sacc[mk][nq][3]); }
;       mx = max3_(mx, shx(mx, 16), mx); mx = max3_(mx, shx(mx, 32), mx);
;       if (!BIAS) mx *= scale_l2;
;       const bool upd = mx > mrun[nq] + 8.f;
;       const float mnew = upd ? mx : mrun[nq];
;       if (__builtin_amdgcn_ballot_w64(upd) != 0) {
;         const float alpha = __builtin_amdgcn_exp2f(mrun[nq] - mnew);
;         lrun[nq] *= alpha;
; #pragma unroll
;         for (int md = 0; md < 8; ++md) { oacc[md][nq][0] *= alpha; oacc[md][nq][1] *= alpha; oacc[md][nq][2] *= alpha; oacc[md][nq][3] *= alpha; }
;       }
;       mrun[nq] = mnew;
;       float ps = 0.f;
; #pragma unroll
;       for (int mk = 0; mk < 4; ++mk)
; #pragma unroll
;         for (int j = 0; j < 4; ++j) {
;           float pe = BIAS ? __builtin_amdgcn_exp2f(sacc[mk][nq][j] - mnew) : __builtin_amdgcn_exp2f(sacc[mk][nq][j] * scale_l2 - mnew);
;           sacc[mk][nq][j] = pe; ps += pe;
;         }
;       lrun[nq] += ps;
; #pragma unroll
;       for (int s2 = 0; s2 < 2; ++s2)
; #pragma unroll
;         for (int i = 0; i < 8; ++i) pf[nq][s2][i] = (hf)sacc[2 * s2 + (i >> 2)][nq][i & 3];
;     ...
;           h4 v0 = *(const h4*)(sVT + ((mh * 4 + m4) * 16 + fr) * 72 + s2 * 32 + fq * 4);
;           h4 v1 = *(const h4*)(sVT + ((mh * 4 + m4) * 16 + fr) * 72 + s2 * 32 + 16 + fq * 4);
;           vf[m4][s2] = __builtin_shufflevector(v0, v1, 0, 1, 2, 3, 4, 5, 6, 7);
.LBB0_1974:
	v_max3_f32 v112, v199, v96, v97
	v_max3_f32 v112, v112, v98, v99
	v_max3_f32 v112, v112, v104, v105
	v_max3_f32 v112, v112, v106, v107
	v_max3_f32 v112, v112, v100, v101
	v_max3_f32 v112, v112, v102, v103
	v_max3_f32 v112, v112, v108, v109
	v_max3_f32 v112, v112, v110, v111
	v_mov_b32_e32 v113, v112
	s_nop 1
	v_permlane16_swap_b32_e32 v113, v112
	v_max_f32_e32 v112, v112, v113
	v_mov_b32_e32 v113, v112
	s_nop 1
	v_permlane32_swap_b32_e32 v113, v112
	v_max_f32_e32 v112, v112, v113
	v_add_f32_e32 v113, 0x41000000, v246
	v_cmp_gt_f32_e32 vcc, v112, v113
	s_nop 1
	v_cndmask_b32_e32 v112, v246, v112, vcc
	s_cbranch_vccz .LBB0_1976
	v_accvgpr_read_b32 v55, a115
	v_accvgpr_read_b32 v51, a127
	v_accvgpr_read_b32 v59, a99
	v_accvgpr_read_b32 v63, a83
	v_accvgpr_read_b32 v64, a60
	v_accvgpr_read_b32 v72, a48
	v_accvgpr_read_b32 v68, a32
	v_accvgpr_read_b32 v76, a20
	v_accvgpr_read_b32 v50, a126
	v_accvgpr_read_b32 v49, a125
	v_accvgpr_read_b32 v48, a124
	v_accvgpr_read_b32 v54, a114
	v_accvgpr_read_b32 v53, a113
	v_accvgpr_read_b32 v52, a112
	v_accvgpr_read_b32 v58, a98
	v_accvgpr_read_b32 v57, a97
	v_accvgpr_read_b32 v56, a96
	v_accvgpr_read_b32 v62, a82
	v_accvgpr_read_b32 v61, a81
	v_accvgpr_read_b32 v60, a80
	v_accvgpr_read_b32 v65, a61
	v_accvgpr_read_b32 v66, a62
	v_accvgpr_read_b32 v67, a63
	v_accvgpr_read_b32 v73, a49
	v_accvgpr_read_b32 v74, a50
	v_accvgpr_read_b32 v75, a51
	v_accvgpr_read_b32 v69, a33
	v_accvgpr_read_b32 v70, a34
	v_accvgpr_read_b32 v71, a35
	v_accvgpr_read_b32 v77, a21
	v_accvgpr_read_b32 v78, a22
	v_accvgpr_read_b32 v79, a23
	v_sub_f32_e32 v113, v246, v112
	v_exp_f32_e32 v114, v113
	s_nop 0
	v_pk_mul_f32 v[76:77], v[76:77], v[114:115] op_sel_hi:[1,0]
	v_pk_mul_f32 v[68:69], v[68:69], v[114:115] op_sel_hi:[1,0]
	v_pk_mul_f32 v[72:73], v[72:73], v[114:115] op_sel_hi:[1,0]
	v_pk_mul_f32 v[64:65], v[64:65], v[114:115] op_sel_hi:[1,0]
	v_pk_mul_f32 v[62:63], v[62:63], v[114:115] op_sel_hi:[1,0]
	v_pk_mul_f32 v[58:59], v[58:59], v[114:115] op_sel_hi:[1,0]
	v_pk_mul_f32 v[54:55], v[54:55], v[114:115] op_sel_hi:[1,0]
	v_pk_mul_f32 v[50:51], v[50:51], v[114:115] op_sel_hi:[1,0]
	v_pk_mul_f32 v[78:79], v[78:79], v[114:115] op_sel_hi:[1,0]
	v_pk_mul_f32 v[70:71], v[70:71], v[114:115] op_sel_hi:[1,0]
	v_pk_mul_f32 v[74:75], v[74:75], v[114:115] op_sel_hi:[1,0]
	v_pk_mul_f32 v[66:67], v[66:67], v[114:115] op_sel_hi:[1,0]
	v_pk_mul_f32 v[60:61], v[60:61], v[114:115] op_sel_hi:[1,0]
	v_pk_mul_f32 v[56:57], v[56:57], v[114:115] op_sel_hi:[1,0]
	v_pk_mul_f32 v[52:53], v[52:53], v[114:115] op_sel_hi:[1,0]
	v_pk_mul_f32 v[48:49], v[48:49], v[114:115] op_sel_hi:[1,0]
	v_accvgpr_write_b32 a115, v55
	v_accvgpr_write_b32 a127, v51
	v_accvgpr_write_b32 a99, v59
	v_accvgpr_write_b32 a83, v63
	v_accvgpr_write_b32 a60, v64
	v_accvgpr_write_b32 a48, v72
	v_accvgpr_write_b32 a32, v68
	v_accvgpr_write_b32 a20, v76
	v_mul_f32_e32 v233, v233, v114
	v_accvgpr_write_b32 a126, v50
	v_accvgpr_write_b32 a125, v49
	v_accvgpr_write_b32 a124, v48
	v_accvgpr_write_b32 a114, v54
	v_accvgpr_write_b32 a113, v53
	v_accvgpr_write_b32 a112, v52
	v_accvgpr_write_b32 a98, v58
	v_accvgpr_write_b32 a97, v57
	v_accvgpr_write_b32 a96, v56
	v_accvgpr_write_b32 a82, v62
	v_accvgpr_write_b32 a81, v61
	v_accvgpr_write_b32 a80, v60
	v_accvgpr_write_b32 a61, v65
	v_accvgpr_write_b32 a62, v66
	v_accvgpr_write_b32 a63, v67
	v_accvgpr_write_b32 a49, v73
	v_accvgpr_write_b32 a50, v74
	v_accvgpr_write_b32 a51, v75
	v_accvgpr_write_b32 a33, v69
	v_accvgpr_write_b32 a34, v70
	v_accvgpr_write_b32 a35, v71
	v_accvgpr_write_b32 a21, v77
	v_accvgpr_write_b32 a22, v78
	v_accvgpr_write_b32 a23, v79
.LBB0_1976:
	v_lshlrev_b32_e32 v113, 1, v238
	v_lshlrev_b32_e32 v114, 1, v237
	v_add3_u32 v113, s95, v113, v114
	v_add_u32_e32 v114, 0x3000, v113
	ds_read2_b64 a[128:131], v114 offset0:128 offset1:132
	v_add_u32_e32 v114, 0x3000, v113
	ds_read2_b64 a[132:135], v114 offset0:136 offset1:140
	v_sub_f32_e32 v48, v128, v144
	v_exp_f32_e32 v48, v48
	v_sub_f32_e32 v50, v129, v144
	v_exp_f32_e32 v50, v50
	v_add_u32_e32 v114, 0x3800, v113
	ds_read2_b64 a[136:139], v114 offset0:160 offset1:164
	v_sub_f32_e32 v51, v130, v144
	v_exp_f32_e32 v51, v51
	v_sub_f32_e32 v52, v131, v144
	v_exp_f32_e32 v52, v52
	v_add_u32_e32 v114, 0x3800, v113
	ds_read2_b64 a[140:143], v114 offset0:168 offset1:172
	v_sub_f32_e32 v53, v140, v144
	v_add_f32_e32 v49, 0, v48
	v_exp_f32_e32 v53, v53
	v_sub_f32_e32 v54, v141, v144
	v_add_u32_e32 v114, 0x4000, v113
	ds_read2_b64 a[144:147], v114 offset0:192 offset1:196
	v_add_f32_e32 v49, v50, v49
	v_exp_f32_e32 v54, v54
	v_sub_f32_e32 v55, v142, v144
	v_add_f32_e32 v49, v51, v49
	v_add_u32_e32 v114, 0x4000, v113
	ds_read2_b64 a[148:151], v114 offset0:200 offset1:204
	v_exp_f32_e32 v55, v55
	v_sub_f32_e32 v56, v143, v144
	v_add_f32_e32 v49, v52, v49
	v_exp_f32_e32 v56, v56
	v_add_u32_e32 v114, 0x4800, v113
	ds_read2_b64 a[152:155], v114 offset0:224 offset1:228
	v_sub_f32_e32 v57, v136, v144
	v_add_f32_e32 v49, v53, v49
	v_exp_f32_e32 v57, v57
	v_sub_f32_e32 v58, v137, v144
	v_add_u32_e32 v114, 0x4800, v113
	ds_read2_b64 a[156:159], v114 offset0:232 offset1:236
	v_add_f32_e32 v49, v54, v49
	v_exp_f32_e32 v58, v58
	v_sub_f32_e32 v59, v138, v144
	v_add_f32_e32 v49, v55, v49
	v_add_u32_e32 v114, 0x5800, v113
	ds_read2_b64 a[160:163], v114 offset1:4
	v_exp_f32_e32 v59, v59
	v_sub_f32_e32 v60, v139, v144
	v_add_f32_e32 v49, v56, v49
	v_exp_f32_e32 v60, v60
	v_add_u32_e32 v114, 0x5800, v113
	ds_read2_b64 a[164:167], v114 offset0:8 offset1:12
	v_sub_f32_e32 v61, v132, v144
	v_add_f32_e32 v49, v57, v49
	v_exp_f32_e32 v61, v61
	v_sub_f32_e32 v62, v133, v144
	v_add_u32_e32 v114, 0x6000, v113
; DI f4 mfma16(h8 a, h8 b, f4 c) { return __builtin_amdgcn_mfma_f32_16x16x32_f16(a, b, c, 0, 0, 0); }
; template <int DQK, bool BIAS>
; __device__ __forceinline__ void attn_pass(const hf* __restrict__ Q, int ldq, const hf* __restrict__ Kp, int ldk, const hf* __restrict__ VT,
;                                           int s0, int L, int q0, float scale_l2, const float* sBias, f4 (&oacc)[8][4], char* smem) {
;     ...
;       float ps = 0.f;
; #pragma unroll
;       for (int mk = 0; mk < 4; ++mk)
; #pragma unroll
;         for (int j = 0; j < 4; ++j) {
;           float pe = BIAS ? __builtin_amdgcn_exp2f(sacc[mk][nq][j] - mnew) : __builtin_amdgcn_exp2f(sacc[mk][nq][j] * scale_l2 - mnew);
;           sacc[mk][nq][j] = pe; ps += pe;
;         }
;       lrun[nq] += ps;
; #pragma unroll
;       for (int s2 = 0; s2 < 2; ++s2)
; #pragma unroll
;         for (int i = 0; i < 8; ++i) pf[nq][s2][i] = (hf)sacc[2 * s2 + (i >> 2)][nq][i & 3];
;     }
; #pragma unroll
;     for (int mh = 0; mh < 2; ++mh) {
;       h8 vf[4][2];
; #pragma unroll
;       for (int m4 = 0; m4 < 4; ++m4)
; #pragma unroll
;         for (int s2 = 0; s2 < 2; ++s2) {
;           h4 v0 = *(const h4*)(sVT + ((mh * 4 + m4) * 16 + fr) * 72 + s2 * 32 + fq * 4);
;           h4 v1 = *(const h4*)(sVT + ((mh * 4 + m4) * 16 + fr) * 72 + s2 * 32 + 16 + fq * 4);
;           vf[m4][s2] = __builtin_shufflevector(v0, v1, 0, 1, 2, 3, 4, 5, 6, 7);
;         }
; #pragma unroll
;       for (int nq = 0; nq < 4; ++nq)
; #pragma unroll
;         for (int m4 = 0; m4 < 4; ++m4) {
;           oacc[mh * 4 + m4][nq] = mfma16(vf[m4][0], pf[nq][0], oacc[mh * 4 + m4][nq]);
;           oacc[mh * 4 + m4][nq] = mfma16(vf[m4][1], pf[nq][1], oacc[mh * 4 + m4][nq]);
;         }
	ds_read2_b64 a[168:171], v114 offset0:32 offset1:36
	v_add_f32_e32 v49, v58, v49
	v_exp_f32_e32 v62, v62
	v_sub_f32_e32 v63, v134, v144
	v_add_f32_e32 v49, v59, v49
	v_add_u32_e32 v114, 0x6000, v113
	ds_read2_b64 a[172:175], v114 offset0:40 offset1:44
	v_exp_f32_e32 v63, v63
	v_sub_f32_e32 v64, v135, v144
	v_add_f32_e32 v49, v60, v49
	v_exp_f32_e32 v64, v64
	v_add_u32_e32 v114, 0x6800, v113
	ds_read2_b64 a[176:179], v114 offset0:64 offset1:68
	v_add_f32_e32 v49, v61, v49
	v_add_f32_e32 v49, v62, v49
	v_add_f32_e32 v49, v63, v49
	v_cvt_pk_f16_f32 v55, v55, v56
	v_add_u32_e32 v114, 0x6800, v113
	ds_read2_b64 a[180:183], v114 offset0:72 offset1:76
	v_sub_f32_e32 v56, v80, v160
	v_add_f32_e32 v49, v64, v49
	v_cvt_pk_f16_f32 v54, v53, v54
	v_cvt_pk_f16_f32 v53, v51, v52
	v_add_u32_e32 v114, 0x7000, v113
	ds_read2_b64 a[184:187], v114 offset0:96 offset1:100
	v_cvt_pk_f16_f32 v52, v48, v50
	v_cvt_pk_f16_f32 v48, v57, v58
	v_exp_f32_e32 v56, v56
	v_sub_f32_e32 v58, v81, v160
	v_add_u32_e32 v114, 0x7000, v113
	ds_read2_b64 a[188:191], v114 offset0:104 offset1:108
	v_add_f32_e32 v242, v49, v242
	v_cvt_pk_f16_f32 v49, v59, v60
	v_exp_f32_e32 v58, v58
	v_sub_f32_e32 v59, v82, v160
	v_exp_f32_e32 v59, v59
	v_sub_f32_e32 v60, v83, v160
	v_cvt_pk_f16_f32 v50, v61, v62
	v_exp_f32_e32 v60, v60
	v_sub_f32_e32 v61, v92, v160
	v_add_f32_e32 v57, 0, v56
	v_exp_f32_e32 v61, v61
	v_sub_f32_e32 v62, v93, v160
	v_cvt_pk_f16_f32 v51, v63, v64
	v_add_f32_e32 v57, v58, v57
	v_exp_f32_e32 v62, v62
	s_waitcnt lgkmcnt(0)
	v_mfma_f32_16x16x32_f16 a[12:15], a[128:131], v[52:55], a[12:15]
	v_sub_f32_e32 v63, v94, v160
	v_add_f32_e32 v57, v59, v57
	v_mfma_f32_16x16x32_f16 a[28:31], a[136:139], v[52:55], a[28:31]
	v_exp_f32_e32 v63, v63
	v_sub_f32_e32 v64, v95, v160
	v_mfma_f32_16x16x32_f16 a[40:43], a[144:147], v[52:55], a[40:43]
	v_sub_f32_e32 v32, v32, v176
	v_add_f32_e32 v57, v60, v57
	v_mfma_f32_16x16x32_f16 a[56:59], a[152:155], v[52:55], a[56:59]
	v_exp_f32_e32 v64, v64
	v_exp_f32_e32 v32, v32
	v_mfma_f32_16x16x32_f16 a[12:15], a[132:135], v[48:51], a[12:15]
	v_sub_f32_e32 v33, v33, v176
	v_add_f32_e32 v57, v61, v57
	v_mfma_f32_16x16x32_f16 a[28:31], a[140:143], v[48:51], a[28:31]
	v_exp_f32_e32 v33, v33
	v_sub_f32_e32 v34, v34, v176
	v_mfma_f32_16x16x32_f16 a[40:43], a[148:151], v[48:51], a[40:43]
	v_add_f32_e32 v57, v62, v57
	v_exp_f32_e32 v34, v34
	v_mfma_f32_16x16x32_f16 a[56:59], a[156:159], v[48:51], a[56:59]
	v_sub_f32_e32 v35, v35, v176
	v_add_f32_e32 v57, v63, v57
	v_mfma_f32_16x16x32_f16 a[72:75], a[160:163], v[52:55], a[72:75]
	v_exp_f32_e32 v35, v35
	v_sub_f32_e32 v44, v44, v176
	v_mfma_f32_16x16x32_f16 a[88:91], a[168:171], v[52:55], a[88:91]
	v_add_f32_e32 v57, v64, v57
	v_sub_f32_e32 v65, v84, v160
	v_mfma_f32_16x16x32_f16 a[108:111], a[176:179], v[52:55], a[108:111]
	v_sub_f32_e32 v66, v85, v160
	v_cvt_pk_f16_f32 v63, v63, v64
	v_mfma_f32_16x16x32_f16 a[120:123], a[184:187], v[52:55], a[120:123]
	v_add_f32_e32 v64, 0, v32
	v_exp_f32_e32 v44, v44
	v_mfma_f32_16x16x32_f16 a[72:75], a[164:167], v[48:51], a[72:75]
	v_sub_f32_e32 v45, v45, v176
	v_exp_f32_e32 v65, v65
	v_mfma_f32_16x16x32_f16 a[88:91], a[172:175], v[48:51], a[88:91]
	v_exp_f32_e32 v66, v66
	v_add_f32_e32 v64, v33, v64
	v_mfma_f32_16x16x32_f16 a[108:111], a[180:183], v[48:51], a[108:111]
	v_exp_f32_e32 v45, v45
	v_sub_f32_e32 v46, v46, v176
	v_mfma_f32_16x16x32_f16 a[120:123], a[188:191], v[48:51], a[120:123]
	v_add_f32_e32 v64, v34, v64
	v_exp_f32_e32 v46, v46
	v_sub_f32_e32 v47, v47, v176
	v_add_f32_e32 v64, v35, v64
	v_exp_f32_e32 v47, v47
	v_sub_f32_e32 v40, v40, v176
	v_add_f32_e32 v64, v44, v64
	v_exp_f32_e32 v40, v40
	v_sub_f32_e32 v41, v41, v176
	v_add_f32_e32 v57, v65, v57
	v_cvt_pk_f16_f32 v62, v61, v62
	v_cvt_pk_f16_f32 v61, v59, v60
	v_cvt_pk_f16_f32 v60, v56, v58
	v_cvt_pk_f16_f32 v56, v65, v66
	v_add_f32_e32 v64, v45, v64
	v_exp_f32_e32 v65, v41
	v_add_f32_e32 v64, v46, v64
	v_add_f32_e32 v64, v47, v64
	v_add_f32_e32 v64, v40, v64
	v_sub_f32_e32 v42, v42, v176
	v_add_f32_e32 v41, v65, v64
	v_exp_f32_e32 v64, v42
	v_sub_f32_e32 v42, v43, v176
	v_add_f32_e32 v57, v66, v57
	v_exp_f32_e32 v66, v42
	v_sub_f32_e32 v36, v36, v176
	v_sub_f32_e32 v37, v37, v176
	v_sub_f32_e32 v67, v86, v160
	v_exp_f32_e32 v36, v36
	v_exp_f32_e32 v37, v37
	v_exp_f32_e32 v67, v67
	v_sub_f32_e32 v68, v87, v160
	v_sub_f32_e32 v38, v38, v176
	v_sub_f32_e32 v39, v39, v176
	v_cvt_pk_f16_f32 v47, v46, v47
	v_cvt_pk_f16_f32 v46, v44, v45
	v_cvt_pk_f16_f32 v44, v32, v33
	v_sub_f32_e32 v32, v96, v112
	v_exp_f32_e32 v68, v68
	v_sub_f32_e32 v69, v88, v160
	v_add_f32_e32 v41, v64, v41
	v_exp_f32_e32 v38, v38
	v_exp_f32_e32 v39, v39
	v_cvt_pk_f16_f32 v45, v34, v35
	v_exp_f32_e32 v32, v32
	v_sub_f32_e32 v34, v97, v112
	v_exp_f32_e32 v69, v69
	v_sub_f32_e32 v70, v89, v160
	v_add_f32_e32 v41, v66, v41
	v_exp_f32_e32 v34, v34
	v_sub_f32_e32 v35, v98, v112
	v_exp_f32_e32 v70, v70
	v_sub_f32_e32 v71, v90, v160
	v_add_f32_e32 v41, v36, v41
	v_cvt_pk_f16_f32 v42, v36, v37
	v_exp_f32_e32 v35, v35
	v_sub_f32_e32 v36, v99, v112
	v_add_f32_e32 v57, v67, v57
	v_exp_f32_e32 v71, v71
	v_sub_f32_e32 v72, v91, v160
	v_add_f32_e32 v41, v37, v41
	v_exp_f32_e32 v36, v36
	v_sub_f32_e32 v37, v104, v112
	v_add_f32_e32 v57, v68, v57
	v_exp_f32_e32 v72, v72
; DI f4 mfma16(h8 a, h8 b, f4 c) { return __builtin_amdgcn_mfma_f32_16x16x32_f16(a, b, c, 0, 0, 0); }
; template <int DQK, bool BIAS>
; __device__ __forceinline__ void attn_pass(const hf* __restrict__ Q, int ldq, const hf* __restrict__ Kp, int ldk, const hf* __restrict__ VT,
;                                           int s0, int L, int q0, float scale_l2, const float* sBias, f4 (&oacc)[8][4], char* smem) {
;     ...
;       float ps = 0.f;
; #pragma unroll
;       for (int mk = 0; mk < 4; ++mk)
; #pragma unroll
;         for (int j = 0; j < 4; ++j) {
;           float pe = BIAS ? __builtin_amdgcn_exp2f(sacc[mk][nq][j] - mnew) : __builtin_amdgcn_exp2f(sacc[mk][nq][j] * scale_l2 - mnew);
;           sacc[mk][nq][j] = pe; ps += pe;
;         }
;       lrun[nq] += ps;
; #pragma unroll
;       for (int s2 = 0; s2 < 2; ++s2)
; #pragma unroll
;         for (int i = 0; i < 8; ++i) pf[nq][s2][i] = (hf)sacc[2 * s2 + (i >> 2)][nq][i & 3];
;     }
; #pragma unroll
;     for (int mh = 0; mh < 2; ++mh) {
;       h8 vf[4][2];
; #pragma unroll
;       for (int m4 = 0; m4 < 4; ++m4)
; #pragma unroll
;         for (int s2 = 0; s2 < 2; ++s2) {
;           h4 v0 = *(const h4*)(sVT + ((mh * 4 + m4) * 16 + fr) * 72 + s2 * 32 + fq * 4);
;           h4 v1 = *(const h4*)(sVT + ((mh * 4 + m4) * 16 + fr) * 72 + s2 * 32 + 16 + fq * 4);
;           vf[m4][s2] = __builtin_shufflevector(v0, v1, 0, 1, 2, 3, 4, 5, 6, 7);
;         }
; #pragma unroll
;       for (int nq = 0; nq < 4; ++nq)
; #pragma unroll
;         for (int m4 = 0; m4 < 4; ++m4) {
;           oacc[mh * 4 + m4][nq] = mfma16(vf[m4][0], pf[nq][0], oacc[mh * 4 + m4][nq]);
;           oacc[mh * 4 + m4][nq] = mfma16(vf[m4][1], pf[nq][1], oacc[mh * 4 + m4][nq]);
;         }
;     }
;     __syncthreads();
	v_add_f32_e32 v41, v38, v41
	v_cvt_pk_f16_f32 v43, v38, v39
	v_add_f32_e32 v33, 0, v32
	v_exp_f32_e32 v37, v37
	v_sub_f32_e32 v38, v105, v112
	v_add_f32_e32 v57, v69, v57
	v_add_f32_e32 v41, v39, v41
	v_add_f32_e32 v33, v34, v33
	v_exp_f32_e32 v38, v38
	v_sub_f32_e32 v39, v106, v112
	v_add_f32_e32 v57, v70, v57
	v_add_f32_e32 v245, v41, v245
	v_cvt_pk_f16_f32 v41, v64, v66
	v_add_f32_e32 v33, v35, v33
	v_exp_f32_e32 v39, v39
	v_sub_f32_e32 v64, v107, v112
	v_add_f32_e32 v57, v71, v57
	v_cvt_pk_f16_f32 v40, v40, v65
	v_add_f32_e32 v33, v36, v33
	v_exp_f32_e32 v64, v64
	v_mfma_f32_16x16x32_f16 a[0:3], a[128:131], v[44:47], a[0:3]
	v_sub_f32_e32 v65, v100, v112
	v_add_f32_e32 v57, v72, v57
	v_mfma_f32_16x16x32_f16 a[8:11], a[136:139], v[44:47], a[8:11]
	v_add_f32_e32 v33, v37, v33
	v_exp_f32_e32 v65, v65
	v_mfma_f32_16x16x32_f16 a[24:27], a[144:147], v[44:47], a[24:27]
	v_sub_f32_e32 v66, v101, v112
	v_add_f32_e32 v243, v57, v243
	v_mfma_f32_16x16x32_f16 a[44:47], a[152:155], v[44:47], a[44:47]
	v_cvt_pk_f16_f32 v57, v67, v68
	v_add_f32_e32 v33, v38, v33
	v_mfma_f32_16x16x32_f16 a[0:3], a[132:135], v[40:43], a[0:3]
	v_exp_f32_e32 v66, v66
	v_sub_f32_e32 v67, v102, v112
	v_mfma_f32_16x16x32_f16 a[8:11], a[140:143], v[40:43], a[8:11]
	v_add_f32_e32 v33, v39, v33
	v_exp_f32_e32 v67, v67
	v_mfma_f32_16x16x32_f16 a[24:27], a[148:151], v[40:43], a[24:27]
	v_sub_f32_e32 v68, v103, v112
	v_cvt_pk_f16_f32 v58, v69, v70
	v_mfma_f32_16x16x32_f16 a[44:47], a[156:159], v[40:43], a[44:47]
	v_add_f32_e32 v33, v64, v33
	v_exp_f32_e32 v68, v68
	v_mfma_f32_16x16x32_f16 a[64:67], a[160:163], v[44:47], a[64:67]
	v_sub_f32_e32 v69, v108, v112
	v_add_f32_e32 v33, v65, v33
	v_mfma_f32_16x16x32_f16 a[76:79], a[168:171], v[44:47], a[76:79]
	v_exp_f32_e32 v69, v69
	v_sub_f32_e32 v70, v109, v112
	v_mfma_f32_16x16x32_f16 a[92:95], a[176:179], v[44:47], a[92:95]
	v_cvt_pk_f16_f32 v59, v71, v72
	v_add_f32_e32 v33, v66, v33
	v_mfma_f32_16x16x32_f16 a[104:107], a[184:187], v[44:47], a[104:107]
	v_exp_f32_e32 v70, v70
	v_sub_f32_e32 v71, v110, v112
	v_mfma_f32_16x16x32_f16 a[64:67], a[164:167], v[40:43], a[64:67]
	v_add_f32_e32 v33, v67, v33
	v_exp_f32_e32 v71, v71
	v_mfma_f32_16x16x32_f16 a[76:79], a[172:175], v[40:43], a[76:79]
	v_sub_f32_e32 v72, v111, v112
	v_add_f32_e32 v33, v68, v33
	v_mfma_f32_16x16x32_f16 a[92:95], a[180:183], v[40:43], a[92:95]
	v_exp_f32_e32 v72, v72
	v_add_f32_e32 v33, v69, v33
	v_mfma_f32_16x16x32_f16 a[104:107], a[188:191], v[40:43], a[104:107]
	v_add_f32_e32 v33, v70, v33
	v_cvt_pk_f16_f32 v39, v39, v64
	v_mfma_f32_16x16x32_f16 a[4:7], a[128:131], v[60:63], a[4:7]
	v_cvt_pk_f16_f32 v38, v37, v38
	v_cvt_pk_f16_f32 v37, v35, v36
	v_mfma_f32_16x16x32_f16 a[16:19], a[136:139], v[60:63], a[16:19]
	v_cvt_pk_f16_f32 v36, v32, v34
	v_cvt_pk_f16_f32 v32, v65, v66
	v_mfma_f32_16x16x32_f16 a[36:39], a[144:147], v[60:63], a[36:39]
	v_add_f32_e32 v33, v71, v33
	v_add_f32_e32 v33, v72, v33
	v_mfma_f32_16x16x32_f16 a[52:55], a[152:155], v[60:63], a[52:55]
	v_add_f32_e32 v233, v33, v233
	v_cvt_pk_f16_f32 v35, v71, v72
	v_mfma_f32_16x16x32_f16 a[4:7], a[132:135], v[56:59], a[4:7]
	v_cvt_pk_f16_f32 v34, v69, v70
	v_cvt_pk_f16_f32 v33, v67, v68
	v_mfma_f32_16x16x32_f16 a[16:19], a[140:143], v[56:59], a[16:19]
	s_nop 1
	s_waitcnt lgkmcnt(0)
	s_barrier
	v_mfma_f32_16x16x32_f16 a[36:39], a[148:151], v[56:59], a[36:39]
	v_mfma_f32_16x16x32_f16 a[52:55], a[156:159], v[56:59], a[52:55]
	v_mfma_f32_16x16x32_f16 a[68:71], a[160:163], v[60:63], a[68:71]
	v_mfma_f32_16x16x32_f16 a[84:87], a[168:171], v[60:63], a[84:87]
	v_mfma_f32_16x16x32_f16 a[100:103], a[176:179], v[60:63], a[100:103]
	v_mfma_f32_16x16x32_f16 a[116:119], a[184:187], v[60:63], a[116:119]
	v_mfma_f32_16x16x32_f16 a[68:71], a[164:167], v[56:59], a[68:71]
	v_mfma_f32_16x16x32_f16 a[84:87], a[172:175], v[56:59], a[84:87]
	v_mfma_f32_16x16x32_f16 a[100:103], a[180:183], v[56:59], a[100:103]
	v_mfma_f32_16x16x32_f16 a[116:119], a[188:191], v[56:59], a[116:119]
	v_mfma_f32_16x16x32_f16 a[20:23], a[128:131], v[36:39], a[20:23]
	v_mfma_f32_16x16x32_f16 a[32:35], a[136:139], v[36:39], a[32:35]
	v_mfma_f32_16x16x32_f16 a[48:51], a[144:147], v[36:39], a[48:51]
	v_mfma_f32_16x16x32_f16 a[60:63], a[152:155], v[36:39], a[60:63]
	v_mfma_f32_16x16x32_f16 a[20:23], a[132:135], v[32:35], a[20:23]
	v_mfma_f32_16x16x32_f16 a[32:35], a[140:143], v[32:35], a[32:35]
	v_mfma_f32_16x16x32_f16 a[48:51], a[148:151], v[32:35], a[48:51]
	v_mfma_f32_16x16x32_f16 a[60:63], a[156:159], v[32:35], a[60:63]
	v_mfma_f32_16x16x32_f16 a[80:83], a[160:163], v[36:39], a[80:83]
	v_mfma_f32_16x16x32_f16 a[96:99], a[168:171], v[36:39], a[96:99]
	v_mfma_f32_16x16x32_f16 a[112:115], a[176:179], v[36:39], a[112:115]
	v_mfma_f32_16x16x32_f16 a[124:127], a[184:187], v[36:39], a[124:127]
	v_mfma_f32_16x16x32_f16 a[80:83], a[164:167], v[32:35], a[80:83]
	v_mfma_f32_16x16x32_f16 a[96:99], a[172:175], v[32:35], a[96:99]
	v_mfma_f32_16x16x32_f16 a[112:115], a[180:183], v[32:35], a[112:115]
	v_mfma_f32_16x16x32_f16 a[124:127], a[188:191], v[32:35], a[124:127]
	s_add_i32 s20, s20, 64
	s_cmp_lg_u32 s73, s94
	s_cbranch_scc0 .LBB0_1978
	v_mov_b32_e32 v246, v112
	v_mov_b32_e32 v247, v144
	v_mov_b32_e32 v253, v160
	v_mov_b32_e32 v198, v176
	s_mov_b32 s16, s94
	s_branch .LBB0_1948

; DI float max3_(float a, float b, float c) { float r; asm("v_max3_f32 %0, %1, %2, %3" : "=v"(r) : "v"(a), "v"(b), "v"(c)); return r; }
; template <int DQK, bool BIAS>
; __device__ __forceinline__ void attn_pass(const hf* __restrict__ Q, int ldq, const hf* __restrict__ Kp, int ldk, const hf* __restrict__ VT,
;                                           int s0, int L, int q0, float scale_l2, const float* sBias, f4 (&oacc)[8][4], char* smem) {
;     ...
;       float mx = -1e30f;
; #pragma unroll
;       for (int mk = 0; mk < 4; ++mk) { mx = max3_(mx, sacc[mk][nq][0], sacc[mk][nq][1]); mx = max3_(mx, sacc[mk][nq][2], sacc[mk][nq][3]); }
;       mx = max3_(mx, shx(mx, 16), mx); mx = max3_(mx, shx(mx, 32), mx);
;       if (!BIAS) mx *= scale_l2;
;       const bool upd = mx > mrun[nq] + 8.f;
;       const float mnew = upd ? mx : mrun[nq];
;       if (__builtin_amdgcn_ballot_w64(upd) != 0) {
;         const float alpha = __builtin_amdgcn_exp2f(mrun[nq] - mnew);
;         lrun[nq] *= alpha;
; #pragma unroll
;         for (int md = 0; md < 8; ++md) { oacc[md][nq][0] *= alpha; oacc[md][nq][1] *= alpha; oacc[md][nq][2] *= alpha; oacc[md][nq][3] *= alpha; }
;       }
.LBB0_2004:
	v_max3_f32 v128, v226, v124, v125
	v_mov_b32_e32 v130, v224
	v_max3_f32 v128, v128, v126, v127
	s_nop 0
	v_max3_f32 v128, v128, v104, v105
	v_lshlrev_b32_e32 v130, 2, v130
	v_max3_f32 v128, v128, v106, v107
	v_bitop3_b32 v130, v130, s23, v227 bitop3:0x6c
	v_max3_f32 v128, v128, v84, v85
	v_max3_f32 v128, v128, v86, v87
	v_max3_f32 v128, v128, v76, v77
	v_max3_f32 v128, v128, v78, v79
	v_mov_b32_e32 v129, v128
	s_nop 1
	v_permlane16_swap_b32_e32 v129, v128
	v_max_f32_e32 v128, v128, v129
	v_mov_b32_e32 v129, v128
	s_nop 1
	v_permlane32_swap_b32_e32 v129, v128
	v_max_f32_e32 v128, v128, v129
	v_add_f32_e32 v130, 0x41000000, v242
	v_mul_f32_e32 v128, 0x3e16c740, v128
	v_cmp_gt_f32_e32 vcc, v128, v130
	s_nop 1
	v_cndmask_b32_e32 v128, v242, v128, vcc
	s_cbranch_vccz .LBB0_2006
	v_accvgpr_read_b32 v95, a115
	v_accvgpr_read_b32 v91, a127
	v_accvgpr_read_b32 v96, a96
	v_accvgpr_read_b32 v100, a80
	v_accvgpr_read_b32 v108, a60
	v_accvgpr_read_b32 v112, a52
	v_accvgpr_read_b32 v116, a36
	v_accvgpr_read_b32 v120, a20
	v_accvgpr_read_b32 v90, a126
	v_accvgpr_read_b32 v89, a125
	v_accvgpr_read_b32 v88, a124
	v_accvgpr_read_b32 v94, a114
	v_accvgpr_read_b32 v93, a113
	v_accvgpr_read_b32 v92, a112
	v_accvgpr_read_b32 v97, a97
	v_accvgpr_read_b32 v98, a98
	v_accvgpr_read_b32 v99, a99
	v_accvgpr_read_b32 v101, a81
	v_accvgpr_read_b32 v102, a82
	v_accvgpr_read_b32 v103, a83
	v_accvgpr_read_b32 v109, a61
	v_accvgpr_read_b32 v110, a62
	v_accvgpr_read_b32 v111, a63
	v_accvgpr_read_b32 v113, a53
	v_accvgpr_read_b32 v114, a54
	v_accvgpr_read_b32 v115, a55
	v_accvgpr_read_b32 v117, a37
	v_accvgpr_read_b32 v118, a38
	v_accvgpr_read_b32 v119, a39
	v_accvgpr_read_b32 v121, a21
	v_accvgpr_read_b32 v122, a22
	v_accvgpr_read_b32 v123, a23
	v_sub_f32_e32 v129, v242, v128
	v_exp_f32_e32 v130, v129
	s_nop 0
	v_pk_mul_f32 v[120:121], v[120:121], v[130:131] op_sel_hi:[1,0]
	v_pk_mul_f32 v[116:117], v[116:117], v[130:131] op_sel_hi:[1,0]
	v_pk_mul_f32 v[112:113], v[112:113], v[130:131] op_sel_hi:[1,0]
	v_pk_mul_f32 v[108:109], v[108:109], v[130:131] op_sel_hi:[1,0]
	v_pk_mul_f32 v[100:101], v[100:101], v[130:131] op_sel_hi:[1,0]
	v_pk_mul_f32 v[96:97], v[96:97], v[130:131] op_sel_hi:[1,0]
	v_pk_mul_f32 v[94:95], v[94:95], v[130:131] op_sel_hi:[1,0]
	v_pk_mul_f32 v[90:91], v[90:91], v[130:131] op_sel_hi:[1,0]
	v_pk_mul_f32 v[122:123], v[122:123], v[130:131] op_sel_hi:[1,0]
	v_pk_mul_f32 v[118:119], v[118:119], v[130:131] op_sel_hi:[1,0]
	v_pk_mul_f32 v[114:115], v[114:115], v[130:131] op_sel_hi:[1,0]
	v_pk_mul_f32 v[110:111], v[110:111], v[130:131] op_sel_hi:[1,0]
	v_pk_mul_f32 v[102:103], v[102:103], v[130:131] op_sel_hi:[1,0]
	v_pk_mul_f32 v[98:99], v[98:99], v[130:131] op_sel_hi:[1,0]
	v_pk_mul_f32 v[92:93], v[92:93], v[130:131] op_sel_hi:[1,0]
	v_pk_mul_f32 v[88:89], v[88:89], v[130:131] op_sel_hi:[1,0]
	v_accvgpr_write_b32 a115, v95
	v_accvgpr_write_b32 a127, v91
	v_accvgpr_write_b32 a96, v96
	v_accvgpr_write_b32 a80, v100
	v_accvgpr_write_b32 a60, v108
	v_accvgpr_write_b32 a52, v112
	v_accvgpr_write_b32 a36, v116
	v_accvgpr_write_b32 a20, v120
	v_mul_f32_e32 v235, v235, v130
	v_accvgpr_write_b32 a126, v90
	v_accvgpr_write_b32 a125, v89
	v_accvgpr_write_b32 a124, v88
	v_accvgpr_write_b32 a114, v94
	v_accvgpr_write_b32 a113, v93
	v_accvgpr_write_b32 a112, v92
	v_accvgpr_write_b32 a97, v97
	v_accvgpr_write_b32 a98, v98
	v_accvgpr_write_b32 a99, v99
	v_accvgpr_write_b32 a81, v101
	v_accvgpr_write_b32 a82, v102
	v_accvgpr_write_b32 a83, v103
	v_accvgpr_write_b32 a61, v109
	v_accvgpr_write_b32 a62, v110
	v_accvgpr_write_b32 a63, v111
	v_accvgpr_write_b32 a53, v113
	v_accvgpr_write_b32 a54, v114
	v_accvgpr_write_b32 a55, v115
	v_accvgpr_write_b32 a37, v117
	v_accvgpr_write_b32 a38, v118
	v_accvgpr_write_b32 a39, v119
	v_accvgpr_write_b32 a21, v121
	v_accvgpr_write_b32 a22, v122
	v_accvgpr_write_b32 a23, v123
